# NSA selected branch: union of the wave's 8 block-selection masks kept in SGPRs; an unselected 32-key sub-tile is skipped after 9 scalar instructions instead of ~35
# speedup vs baseline: 1.0081x; 1.0017x over previous
; DI void nsa_phase(int wv, const Params& P, LAS unsigned char* lds) {
;     ...
;           for (int i = 0; i < 16; ++i) { out[0][i] += g0 * o[0][i]; out[1][i] += g0 * o[1][i]; } }
;         asm volatile("s_waitcnt lgkmcnt(0)" ::: "memory");
;         for (int tk = 0; tk < 8; ++tk) { const int tt = t0 + tk, cur = tt >> 6; unsigned long long mlo, mhi;
;             if (cur + 1 <= 16) { mlo = (1ull << (cur + 1)) - 1ull; mhi = 0ull; }
;             else { const int j0 = lane, j1 = lane + 64;
;                 const float s0 = imp[tk * 128 + j0], s1 = imp[tk * 128 + j1];
;                 const unsigned k0 = (j0 > cur) ? 0u : ((j0 == 0 || j0 == cur || j0 == cur - 1) ? 0x7f000000u : __float_as_uint(s0) + 1u);
;                 const unsigned k1 = (j1 > cur) ? 0u : ((j1 == cur || j1 == cur - 1) ? 0x7f000000u : __float_as_uint(s1) + 1u);
;                 unsigned T = 0u;
; #pragma unroll 1
;     ...
;                     const int cnt = __builtin_popcountll(__builtin_amdgcn_ballot_w64(k0 >= cand)) + __builtin_popcountll(__builtin_amdgcn_ballot_w64(k1 >= cand)); if (cnt >= 16) T = cand; }
;                 mlo = __builtin_amdgcn_ballot_w64(k0 > T); mhi = __builtin_amdgcn_ballot_w64(k1 > T);
;                 int need = 16 - __builtin_popcountll(mlo) - __builtin_popcountll(mhi);
;                 unsigned long long elo = __builtin_amdgcn_ballot_w64(k0 == T), ehi = __builtin_amdgcn_ballot_w64(k1 == T);
;     ...
;             if (lane == 0) { selm[tk * 2] = mlo; selm[tk * 2 + 1] = mhi; } }
;         asm volatile("s_waitcnt lgkmcnt(0)" ::: "memory");
;         const unsigned long long mylo = selm[tok * 2], myhi = selm[tok * 2 + 1];
; #pragma unroll 1
;         for (int br = 0; br < 2; ++br) {
;             const bf16_t* Kb = (br ? KW : KS) + (size_t)bh * SEQ * 64; const bf16_t* Vb = (br ? VWT : VST) + (size_t)bh * 64 * SEQ;
;             const int ktb = br ? (((t0b - 511 > 0) ? (t0b - 511) : 0) >> 5) : 0, kte = ((t0b + 63) >> 5) + 1, nt = kte - ktb;
;             const int nst = (nt + 3) >> 2;
;             const bf16_t* gsrc = (isV ? (Vb + (size_t)(ldr >> 4) * SEQ + (ldr & 15) * 8) : (Kb + (size_t)(ldr >> 3) * 64 + (ldr & 7) * 8)) + (size_t)ktb * (isV ? 32 : 32 * 64);
;             const size_t gj = isV ? (size_t)16 * SEQ : (size_t)32 * 64, gstage = isV ? 128 : 128 * 64;
.LBB0_1563:
	s_or_b64 exec, exec, s[10:11]
	s_waitcnt lgkmcnt(0)
	ds_read_b128 v[98:101], v205 offset:32768
	s_max_i32 s12, s72, 0x1ff
	s_lshl_b64 s[10:11], s[78:79], 20
	s_addk_i32 s12, 0xfe01
	s_lshl_b32 s31, s67, 1
	s_waitcnt vmcnt(0) lgkmcnt(0)
	v_readlane_b32 s98, v98, 0
	v_readlane_b32 s99, v99, 0
	v_readlane_b32 s100, v100, 0
	v_readlane_b32 s101, v101, 0
	v_readlane_b32 vcc_lo, v98, 4
	s_or_b32 s98, s98, vcc_lo
	v_readlane_b32 vcc_lo, v99, 4
	s_or_b32 s99, s99, vcc_lo
	v_readlane_b32 vcc_lo, v100, 4
	s_or_b32 s100, s100, vcc_lo
	v_readlane_b32 vcc_lo, v101, 4
	s_or_b32 s101, s101, vcc_lo
	v_readlane_b32 vcc_lo, v98, 8
	s_or_b32 s98, s98, vcc_lo
	v_readlane_b32 vcc_lo, v99, 8
	s_or_b32 s99, s99, vcc_lo
	v_readlane_b32 vcc_lo, v100, 8
	s_or_b32 s100, s100, vcc_lo
	v_readlane_b32 vcc_lo, v101, 8
	s_or_b32 s101, s101, vcc_lo
	v_readlane_b32 vcc_lo, v98, 12
	s_or_b32 s98, s98, vcc_lo
	v_readlane_b32 vcc_lo, v99, 12
	s_or_b32 s99, s99, vcc_lo
	v_readlane_b32 vcc_lo, v100, 12
	s_or_b32 s100, s100, vcc_lo
	v_readlane_b32 vcc_lo, v101, 12
	s_or_b32 s101, s101, vcc_lo
	v_readlane_b32 vcc_lo, v98, 16
	s_or_b32 s98, s98, vcc_lo
	v_readlane_b32 vcc_lo, v99, 16
	s_or_b32 s99, s99, vcc_lo
	v_readlane_b32 vcc_lo, v100, 16
	s_or_b32 s100, s100, vcc_lo
	v_readlane_b32 vcc_lo, v101, 16
	s_or_b32 s101, s101, vcc_lo
	v_readlane_b32 vcc_lo, v98, 20
	s_or_b32 s98, s98, vcc_lo
	v_readlane_b32 vcc_lo, v99, 20
	s_or_b32 s99, s99, vcc_lo
	v_readlane_b32 vcc_lo, v100, 20
	s_or_b32 s100, s100, vcc_lo
	v_readlane_b32 vcc_lo, v101, 20
	s_or_b32 s101, s101, vcc_lo
	v_readlane_b32 vcc_lo, v98, 24
	s_or_b32 s98, s98, vcc_lo
	v_readlane_b32 vcc_lo, v99, 24
	s_or_b32 s99, s99, vcc_lo
	v_readlane_b32 vcc_lo, v100, 24
	s_or_b32 s100, s100, vcc_lo
	v_readlane_b32 vcc_lo, v101, 24
	s_or_b32 s101, s101, vcc_lo
	v_readlane_b32 vcc_lo, v98, 28
	s_or_b32 s98, s98, vcc_lo
	v_readlane_b32 vcc_lo, v99, 28
	s_or_b32 s99, s99, vcc_lo
	v_readlane_b32 vcc_lo, v100, 28
	s_or_b32 s100, s100, vcc_lo
	v_readlane_b32 vcc_lo, v101, 28
	s_or_b32 s101, s101, vcc_lo
	v_pk_fma_f32 v[154:155], v[118:119], v[32:33], 0 op_sel_hi:[0,1,0]
	v_pk_fma_f32 v[158:159], v[118:119], v[30:31], 0 op_sel_hi:[0,1,0]
	v_pk_fma_f32 v[162:163], v[118:119], v[28:29], 0 op_sel_hi:[0,1,0]
	v_pk_fma_f32 v[166:167], v[118:119], v[26:27], 0 op_sel_hi:[0,1,0]
	v_pk_fma_f32 v[170:171], v[118:119], v[24:25], 0 op_sel_hi:[0,1,0]
	v_pk_fma_f32 v[174:175], v[118:119], v[22:23], 0 op_sel_hi:[0,1,0]
	v_pk_fma_f32 v[178:179], v[118:119], v[20:21], 0 op_sel_hi:[0,1,0]
	v_pk_fma_f32 v[182:183], v[118:119], v[18:19], 0 op_sel_hi:[0,1,0]
	v_pk_fma_f32 v[156:157], v[118:119], v[16:17], 0 op_sel_hi:[0,1,0]
	v_pk_fma_f32 v[160:161], v[118:119], v[14:15], 0 op_sel_hi:[0,1,0]
	v_pk_fma_f32 v[164:165], v[118:119], v[12:13], 0 op_sel_hi:[0,1,0]
	v_pk_fma_f32 v[168:169], v[118:119], v[10:11], 0 op_sel_hi:[0,1,0]
	v_pk_fma_f32 v[172:173], v[118:119], v[8:9], 0 op_sel_hi:[0,1,0]
	v_pk_fma_f32 v[176:177], v[118:119], v[6:7], 0 op_sel_hi:[0,1,0]
	v_pk_fma_f32 v[180:181], v[118:119], v[4:5], 0 op_sel_hi:[0,1,0]
	v_pk_fma_f32 v[184:185], v[118:119], v[2:3], 0 op_sel_hi:[0,1,0]
	s_lshr_b32 s30, s12, 5
	s_add_i32 s31, s31, 2
	v_lshl_add_u64 v[186:187], v[128:129], 0, s[10:11]
	v_lshl_add_u64 v[188:189], v[130:131], 0, s[10:11]
	s_mov_b64 s[16:17], -1
	s_branch .LBB0_1565

; #define LAS __attribute__((address_space(3)))
; #define NSA_LOAD(si_) _Pragma("unroll") for (int j_ = 0; j_ < 4; ++j_) pre[j_] = *(const u32x4*)(gsrc + (size_t)(si_) * gstage + j_ * gj)
; #define NSA_STORE(buf_) _Pragma("unroll") for (int j_ = 0; j_ < 4; ++j_) *(LAS u32x4*)(tiles + (buf_) * STAGE_BYTES_A + loff + j_ * lj) = pre[j_]
; DI void nsa_phase(int wv, const Params& P, LAS unsigned char* lds) {
;     ...
;             for (int si = 0; si < nst; ++si) { const int cur = si & 1;
;                 if (si + 1 < nst) { NSA_STORE(cur ^ 1); if (si + 2 < nst) { NSA_LOAD(si + 2); } }
; #pragma unroll 1
;                 for (int sub = 0; sub < 4; ++sub) { const int ti = si * 4 + sub; if (ti >= nt) break; const int key0 = (ktb + ti) * 32;
;                     const bool rel = br ? (key0 <= t0 + 7 && key0 + 31 + 512 > t0) : (key0 <= t0 + 7);
;                     if (rel) {
;                         const LAS bf16_t* Kt = (const LAS bf16_t*)(tiles + cur * STAGE_BYTES_A) + sub * 32 * KT_LD; const LAS bf16_t* Vt = (const LAS bf16_t*)(tiles + cur * STAGE_BYTES_A + STG_K_BYTES) + sub * 32;
;                         const int jb = key0 >> 6; const bool mine = br ? true : ((jb < 64) ? ((mylo >> jb) & 1ull) : ((myhi >> (jb - 64)) & 1ull));
;                         const bool full = br ? (key0 + 31 <= t0 && key0 + 512 > t0 + 7) : (key0 + 31 <= t0);
;                         if (__builtin_amdgcn_ballot_w64(mine) == 0ull) {   }
.LBB0_1578:
	s_cmp_ge_i32 s41, s35
	s_mov_b64 s[10:11], -1
	s_cbranch_scc1 .LBB0_1577
	s_cmp_eq_u64 s[16:17], 0
	s_cbranch_scc1 .Lnsa_nochk
	s_add_i32 s10, s34, s41
	s_lshr_b32 s14, s10, 1
	s_cmpk_gt_u32 s10, 0x7f
	s_cselect_b64 s[10:11], s[100:101], s[98:99]
	s_lshr_b64 s[10:11], s[10:11], s14
	s_bitcmp0_b32 s10, 0
	s_cbranch_scc1 .LBB0_1607
.Lnsa_nochk:
	s_add_i32 s28, s37, s40
	v_cndmask_b32_e64 v0, 0, 1, s[18:19]
	v_cmp_ne_u32_e64 s[12:13], 1, v0
	s_andn2_b64 vcc, exec, s[18:19]
	v_cmp_le_i32_e64 s[10:11], s28, v149
	s_cbranch_vccnz .LBB0_1583
	s_mov_b64 s[22:23], 0
	s_mov_b64 s[24:25], 0
	s_and_saveexec_b64 s[26:27], s[10:11]
	s_add_i32 s14, s28, 0x21f
	s_mov_b64 s[24:25], exec
	v_cmp_gt_i32_e64 s[14:15], s14, v147
	s_or_b64 exec, exec, s[26:27]
	s_and_b64 vcc, exec, s[22:23]
	s_cbranch_vccnz .LBB0_1584
	s_branch .LBB0_1585

; #define LAS __attribute__((address_space(3)))
; __global__ void __launch_bounds__(NTHREADS, 2) mega_fwd(Params P) {
;     extern __shared__ __attribute__((aligned(16))) unsigned char lds_raw[];
;     LAS unsigned char* lds = (LAS unsigned char*)lds_raw;
;     cg::grid_group grid = cg::this_grid();
;     const int wv = __builtin_amdgcn_readfirstlane(threadIdx.x >> 6);
	.amdhsa_kernel _Z8mega_fwd6Params
		.amdhsa_group_segment_fixed_size 0
		.amdhsa_private_segment_fixed_size 0
		.amdhsa_kernarg_size 3696
		.amdhsa_user_sgpr_count 2
		.amdhsa_user_sgpr_dispatch_ptr 0
		.amdhsa_user_sgpr_queue_ptr 0
		.amdhsa_user_sgpr_kernarg_segment_ptr 1
		.amdhsa_user_sgpr_dispatch_id 0
		.amdhsa_user_sgpr_kernarg_preload_length 0
		.amdhsa_user_sgpr_kernarg_preload_offset 0
		.amdhsa_user_sgpr_private_segment_size 0
		.amdhsa_uses_dynamic_stack 0
		.amdhsa_enable_private_segment 0
		.amdhsa_system_sgpr_workgroup_id_x 1
		.amdhsa_system_sgpr_workgroup_id_y 0
		.amdhsa_system_sgpr_workgroup_id_z 0
		.amdhsa_system_sgpr_workgroup_info 0
		.amdhsa_system_vgpr_workitem_id 2
		.amdhsa_next_free_vgpr 253
		.amdhsa_next_free_sgpr 102
		.amdhsa_accum_offset 256
		.amdhsa_reserve_vcc 1
		.amdhsa_float_round_mode_32 0
		.amdhsa_float_round_mode_16_64 0
		.amdhsa_float_denorm_mode_32 3
		.amdhsa_float_denorm_mode_16_64 3
		.amdhsa_dx10_clamp 1
		.amdhsa_ieee_mode 1
		.amdhsa_fp16_overflow 0
		.amdhsa_tg_split 0
		.amdhsa_exception_fp_ieee_invalid_op 0
		.amdhsa_exception_fp_denorm_src 0
		.amdhsa_exception_fp_ieee_div_zero 0
		.amdhsa_exception_fp_ieee_overflow 0
		.amdhsa_exception_fp_ieee_underflow 0
		.amdhsa_exception_fp_ieee_inexact 0
		.amdhsa_exception_int_div_zero 0
	.end_amdhsa_kernel

; #define LAS __attribute__((address_space(3)))
; __global__ void __launch_bounds__(NTHREADS, 2) mega_fwd(Params P) {
;     extern __shared__ __attribute__((aligned(16))) unsigned char lds_raw[];
;     LAS unsigned char* lds = (LAS unsigned char*)lds_raw;
;     cg::grid_group grid = cg::this_grid();
;     const int wv = __builtin_amdgcn_readfirstlane(threadIdx.x >> 6);
.Lfunc_end0:
	.size	_Z8mega_fwd6Params, .Lfunc_end0-_Z8mega_fwd6Params
	.set _Z8mega_fwd6Params.num_vgpr, 253
	.set _Z8mega_fwd6Params.num_agpr, 0
	.set _Z8mega_fwd6Params.numbered_sgpr, 102
	.set _Z8mega_fwd6Params.num_named_barrier, 0
	.set _Z8mega_fwd6Params.private_seg_size, 0
	.set _Z8mega_fwd6Params.uses_vcc, 1
	.set _Z8mega_fwd6Params.uses_flat_scratch, 0
	.set _Z8mega_fwd6Params.has_dyn_sized_stack, 0
	.set _Z8mega_fwd6Params.has_recursion, 0
	.set _Z8mega_fwd6Params.has_indirect_call, 0

; #define LAS __attribute__((address_space(3)))
; __global__ void __launch_bounds__(NTHREADS, 2) mega_fwd(Params P) {
;     extern __shared__ __attribute__((aligned(16))) unsigned char lds_raw[];
;     LAS unsigned char* lds = (LAS unsigned char*)lds_raw;
;     cg::grid_group grid = cg::this_grid();
;     const int wv = __builtin_amdgcn_readfirstlane(threadIdx.x >> 6);
amdhsa.kernels:
  - .agpr_count:     0
    .args:
      - .offset:         0
        .size:           3440
        .value_kind:     by_value
      - .offset:         3440
        .size:           4
        .value_kind:     hidden_block_count_x
      - .offset:         3444
        .size:           4
        .value_kind:     hidden_block_count_y
      - .offset:         3448
        .size:           4
        .value_kind:     hidden_block_count_z
      - .offset:         3452
        .size:           2
        .value_kind:     hidden_group_size_x
      - .offset:         3454
        .size:           2
        .value_kind:     hidden_group_size_y
      - .offset:         3456
        .size:           2
        .value_kind:     hidden_group_size_z
      - .offset:         3458
        .size:           2
        .value_kind:     hidden_remainder_x
      - .offset:         3460
        .size:           2
        .value_kind:     hidden_remainder_y
      - .offset:         3462
        .size:           2
        .value_kind:     hidden_remainder_z
      - .offset:         3480
        .size:           8
        .value_kind:     hidden_global_offset_x
      - .offset:         3488
        .size:           8
        .value_kind:     hidden_global_offset_y
      - .offset:         3496
        .size:           8
        .value_kind:     hidden_global_offset_z
      - .offset:         3504
        .size:           2
        .value_kind:     hidden_grid_dims
      - .offset:         3528
        .size:           8
        .value_kind:     hidden_multigrid_sync_arg
      - .offset:         3560
        .size:           4
        .value_kind:     hidden_dynamic_lds_size
    .group_segment_fixed_size: 0
    .kernarg_segment_align: 8
    .kernarg_segment_size: 3696
    .language:       OpenCL C
    .language_version:
      - 2
      - 0
    .max_flat_workgroup_size: 512
    .name:           _Z8mega_fwd6Params
    .private_segment_fixed_size: 0
    .sgpr_count:     108
    .sgpr_spill_count: 35
    .symbol:         _Z8mega_fwd6Params.kd
    .uniform_work_group_size: 1
    .uses_dynamic_stack: false
    .vgpr_count:     253
    .vgpr_spill_count: 0
    .wavefront_size: 64
